# attention key loop versioned: tiles entirely before the wave's queries run a body without the causal-mask index adds / compares / selects (diagonal tiles keep the masked body)
# speedup vs baseline: 1.0121x; 1.0106x over previous
.LBB0_931:
	s_mov_b64 s[4:5], 0
	s_add_i32 s8, s3, 0xffffff80
	s_add_u32 s4, s96, s4
	s_addc_u32 s5, s97, s5
	s_and_b32 s9, s8, 0xff
	v_mov_b32_e32 v6, v176
	s_lshl_b32 s6, s9, 13
	s_add_u32 s6, s4, s6
	v_lshlrev_b32_e32 v4, 2, v6
	s_addc_u32 s7, s5, 0
	v_ashrrev_i32_e32 v5, 31, v4
	v_lshl_add_u64 v[0:1], v[4:5], 2, s[6:7]
	s_mov_b32 s6, 0x1a00000
	v_add_co_u32_e32 v0, vcc, s6, v0
	s_nop 1
	v_addc_co_u32_e32 v1, vcc, 0, v1, vcc
	s_barrier
	global_load_dwordx4 v[0:3], v[0:1], off
	v_cmp_lt_i32_e32 vcc, v181, v180
	s_waitcnt vmcnt(0)
	v_add_f32_e32 v1, v0, v1
	v_cndmask_b32_e32 v5, v181, v171, vcc
	v_add_f32_e32 v2, v2, v1
	v_lshlrev_b32_e32 v5, 2, v5
	v_add_f32_e32 v3, v3, v2
	ds_bpermute_b32 v5, v5, v3
	v_cmp_lt_i32_e32 vcc, v182, v180
	s_waitcnt lgkmcnt(0)
	v_add_f32_e32 v5, v3, v5
	v_cndmask_b32_e32 v7, v182, v171, vcc
	v_lshlrev_b32_e32 v8, 2, v7
	v_and_b32_e32 v7, 63, v6
	v_cmp_eq_u32_e32 vcc, 0, v7
	s_nop 1
	v_cndmask_b32_e32 v5, v5, v3, vcc
	ds_bpermute_b32 v8, v8, v5
	v_cmp_lt_i32_e32 vcc, v183, v180
	s_waitcnt lgkmcnt(0)
	v_add_f32_e32 v8, v5, v8
	v_cndmask_b32_e32 v9, v183, v171, vcc
	v_cmp_gt_u32_e32 vcc, 2, v7
	v_lshlrev_b32_e32 v9, 2, v9
	s_nop 0
	v_cndmask_b32_e32 v5, v8, v5, vcc
	ds_bpermute_b32 v8, v9, v5
	v_cmp_lt_i32_e32 vcc, v184, v180
	s_waitcnt lgkmcnt(0)
	v_add_f32_e32 v8, v5, v8
	v_cndmask_b32_e32 v9, v184, v171, vcc
	v_cmp_gt_u32_e32 vcc, 4, v7
	v_lshlrev_b32_e32 v9, 2, v9
	s_nop 0
	v_cndmask_b32_e32 v5, v8, v5, vcc
	ds_bpermute_b32 v8, v9, v5
	v_cmp_lt_i32_e32 vcc, v185, v180
	s_waitcnt lgkmcnt(0)
	v_add_f32_e32 v8, v5, v8
	v_cndmask_b32_e32 v9, v185, v171, vcc
	v_cmp_gt_u32_e32 vcc, 8, v7
	v_lshlrev_b32_e32 v9, 2, v9
	s_nop 0
	v_cndmask_b32_e32 v5, v8, v5, vcc
	ds_bpermute_b32 v8, v9, v5
	v_cmp_lt_i32_e32 vcc, v186, v180
	s_waitcnt lgkmcnt(0)
	v_add_f32_e32 v8, v5, v8
	v_cndmask_b32_e32 v9, v186, v171, vcc
	v_cmp_gt_u32_e32 vcc, 16, v7
	v_lshlrev_b32_e32 v9, 2, v9
	s_nop 0
	v_cndmask_b32_e32 v8, v8, v5, vcc
	ds_bpermute_b32 v9, v9, v8
	v_ashrrev_i32_e32 v5, 6, v6
	v_cmp_eq_u32_e32 vcc, 63, v7
	s_waitcnt lgkmcnt(0)
	v_add_f32_e32 v9, v8, v9
	s_and_saveexec_b64 s[6:7], vcc
	v_lshlrev_b32_e32 v10, 2, v5
	ds_write_b32 v10, v9 offset:26624
	s_or_b64 exec, exec, s[6:7]
	v_cmp_gt_u32_e32 vcc, 32, v7
	v_lshrrev_b32_e32 v16, 5, v7
	s_waitcnt lgkmcnt(0)
	v_cndmask_b32_e32 v7, v9, v8, vcc
	s_barrier
	ds_read_b128 v[8:11], v137 offset:26624
	ds_read_b128 v[12:15], v137 offset:26640
	v_cmp_lt_i32_e32 vcc, 0, v5
	v_sub_f32_e32 v7, v7, v3
	s_andn2_b32 s6, 0x700, s8
	s_waitcnt lgkmcnt(1)
	v_cndmask_b32_e32 v8, 0, v8, vcc
	v_cmp_lt_i32_e32 vcc, 1, v5
	v_add_f32_e32 v7, v7, v8
	v_and_b32_e32 v17, 31, v6
	v_cndmask_b32_e32 v8, 0, v9, vcc
	v_cmp_lt_i32_e32 vcc, 2, v5
	v_add_f32_e32 v7, v7, v8
	v_lshlrev_b32_e32 v4, 2, v4
	v_cndmask_b32_e32 v8, 0, v10, vcc
	v_cmp_lt_i32_e32 vcc, 3, v5
	v_add_f32_e32 v7, v7, v8
	v_lshlrev_b32_e32 v136, 4, v16
	v_cndmask_b32_e32 v8, 0, v11, vcc
	v_cmp_lt_i32_e32 vcc, 4, v5
	v_add_f32_e32 v7, v7, v8
	v_mov_b32_e32 v100, 0
	s_waitcnt lgkmcnt(0)
	v_cndmask_b32_e32 v8, 0, v12, vcc
	v_cmp_lt_i32_e32 vcc, 5, v5
	v_add_f32_e32 v7, v7, v8
	v_lshl_add_u32 v12, v5, 5, s6
	v_cndmask_b32_e32 v8, 0, v13, vcc
	v_cmp_lt_i32_e32 vcc, 6, v5
	v_add_f32_e32 v7, v7, v8
	s_lshl_b32 s6, s8, 8
	v_cndmask_b32_e32 v8, 0, v14, vcc
	v_cmp_lt_i32_e32 vcc, 7, v5
	v_add_f32_e32 v7, v7, v8
	v_or_b32_e32 v96, v12, v17
	v_cndmask_b32_e32 v8, 0, v15, vcc
	v_add_f32_e32 v8, v7, v8
	v_pk_add_f32 v[0:1], v[0:1], v[8:9] op_sel_hi:[1,0]
	v_pk_add_f32 v[2:3], v[2:3], v[8:9] op_sel_hi:[1,0]
	s_and_b32 s10, s6, 0xf800
	ds_write_b128 v4, v[0:3]
	v_add_u32_e32 v0, s10, v96
	v_ashrrev_i32_e32 v1, 31, v0
	s_lshl_b32 s6, s8, 6
	v_lshlrev_b64 v[0:1], 9, v[0:1]
	s_and_b32 s11, s6, 0x1c0
	v_or_b32_e32 v0, s11, v0
	v_lshl_add_u64 v[88:89], v[0:1], 1, s[4:5]
	v_lshl_add_u64 v[0:1], v[88:89], 0, v[136:137]
	s_mov_b64 s[6:7], 0x30000000
	v_lshl_add_u64 v[2:3], v[0:1], 0, s[6:7]
	s_brev_b32 s6, 12
	v_add_co_u32_e32 v0, vcc, s6, v0
	s_waitcnt lgkmcnt(0)
	s_barrier
	v_addc_co_u32_e32 v1, vcc, 0, v1, vcc
	global_load_dwordx4 v[64:67], v[2:3], off offset:32
	global_load_dwordx4 v[68:71], v[2:3], off offset:64
	global_load_dwordx4 v[72:75], v[0:1], off
	global_load_dwordx4 v[76:79], v[2:3], off offset:96
	v_ashrrev_i32_e32 v0, 3, v6
	v_add_u32_e32 v2, s10, v0
	s_lshl_b32 s6, s9, 18
	v_ashrrev_i32_e32 v3, 31, v2
	s_add_u32 s6, s4, s6
	v_lshlrev_b64 v[2:3], 10, v[2:3]
	s_addc_u32 s7, s5, 0
	v_lshl_add_u64 v[2:3], s[4:5], 0, v[2:3]
	s_lshl_b32 s88, s11, 1
	v_lshlrev_b32_e32 v1, 4, v6
	v_lshl_add_u64 v[2:3], v[2:3], 0, s[88:89]
	v_and_b32_e32 v4, 0x70, v1
	v_mov_b32_e32 v5, v137
	v_ashrrev_i32_e32 v1, 31, v0
	v_lshl_add_u64 v[2:3], v[2:3], 0, v[4:5]
	v_lshlrev_b64 v[6:7], 12, v[0:1]
	s_brev_b32 s4, 36
	v_lshl_add_u64 v[6:7], s[6:7], 0, v[6:7]
	v_add_co_u32_e32 v8, vcc, s4, v2
	v_lshl_add_u64 v[6:7], v[6:7], 0, v[4:5]
	s_nop 0
	v_addc_co_u32_e32 v9, vcc, 0, v3, vcc
	s_brev_b32 s4, 44
	v_add_co_u32_e32 v10, vcc, s4, v6
	s_lshr_b32 s4, s8, 6
	s_nop 0
	v_addc_co_u32_e32 v11, vcc, 0, v7, vcc
	global_load_dwordx4 v[80:83], v[8:9], off
	global_load_dwordx4 v[84:87], v[10:11], off
	s_and_b32 s4, s4, 28
	s_sub_i32 s11, 32, s4
	s_mov_b64 s[4:5], 0x24000000
	v_lshl_add_u64 v[90:91], v[2:3], 0, s[4:5]
	s_mov_b64 s[4:5], 0x34000000
	v_lshlrev_b32_e32 v5, 2, v96
	v_lshl_add_u64 v[92:93], v[6:7], 0, s[4:5]
	s_movk_i32 s4, 0x90
	v_lshlrev_b32_e32 v1, 3, v16
	ds_read_b32 v97, v5
	v_mad_u64_u32 v[94:95], s[4:5], v0, s4, v[4:5]
	v_lshlrev_b32_e32 v95, 2, v16
	v_sub_u32_e32 v16, v136, v1
	v_mul_u32_u24_e32 v17, 0x90, v17
	v_cmp_lt_i32_e32 vcc, v177, v178
	v_mov_b32_e32 v14, v137
	v_mov_b32_e32 v15, v137
	v_cndmask_b32_e32 v0, v171, v177, vcc
	v_add_u32_e32 v16, v16, v17
	v_or_b32_e32 v98, 31, v12
	v_lshlrev_b32_e32 v99, 2, v0
	v_mov_b32_e32 v0, v137
	v_mov_b32_e32 v1, v137
	v_mov_b32_e32 v2, v137
	v_mov_b32_e32 v3, v137
	v_mov_b32_e32 v4, v137
	v_mov_b32_e32 v5, v137
	v_mov_b32_e32 v6, v137
	v_mov_b32_e32 v7, v137
	v_mov_b32_e32 v8, v137
	v_mov_b32_e32 v9, v137
	v_mov_b32_e32 v10, v137
	v_mov_b32_e32 v11, v137
	v_mov_b32_e32 v12, v137
	v_mov_b32_e32 v13, v137
	v_add_u32_e32 v101, v136, v17
	v_add_u32_e32 v102, 0x4000, v16
	v_add_u32_e32 v103, 0x5000, v16
	v_mov_b64_e32 v[30:31], v[14:15]
	s_mov_b32 s10, 0
	v_mov_b32_e32 v105, 0xf149f2ca
	s_mov_b64 s[4:5], 0
	v_mov_b32_e32 v104, v136
	v_mov_b64_e32 v[28:29], v[12:13]
	v_mov_b64_e32 v[26:27], v[10:11]
	v_mov_b64_e32 v[24:25], v[8:9]
	v_mov_b64_e32 v[22:23], v[6:7]
	v_mov_b64_e32 v[20:21], v[4:5]
	v_mov_b64_e32 v[18:19], v[2:3]
	v_mov_b64_e32 v[16:17], v[0:1]
	v_readfirstlane_b32 s100, v98
	s_branch .LBB0_935

.LBB0_935:
	s_mov_b64 s[8:9], s[4:5]
	s_add_u32 s4, s8, 1
	s_addc_u32 s5, s9, 0
	s_cmp_ge_u32 s4, s11
	s_cselect_b64 s[6:7], -1, 0
	s_cmp_lt_u32 s4, s11
	s_cselect_b64 s[12:13], -1, 0
	v_cndmask_b32_e64 v32, 0, 1, s[12:13]
	v_mov_b32_e32 v33, s89
	v_lshl_add_u64 v[32:33], s[8:9], 0, v[32:33]
	v_lshlrev_b64 v[34:35], 16, v[32:33]
	v_lshl_add_u64 v[34:35], v[90:91], 0, v[34:35]
	v_lshlrev_b32_e32 v136, 6, v32
	s_waitcnt lgkmcnt(0)
	s_barrier
	s_waitcnt vmcnt(1)
	ds_write_b128 v94, v[80:83] offset:8192
	s_waitcnt vmcnt(0)
	ds_write_b128 v94, v[84:87] offset:17408
	s_waitcnt lgkmcnt(0)
	s_barrier
	v_lshl_add_u64 v[32:33], v[136:137], 1, v[92:93]
	global_load_dwordx4 v[80:83], v[34:35], off
	global_load_dwordx4 v[84:87], v[32:33], off
	v_cmp_le_i32_e32 vcc, s10, v98
	s_and_saveexec_b64 s[8:9], vcc
	s_cbranch_execz .LBB0_934
	s_add_i32 s101, s10, 94
	s_cmp_le_i32 s101, s100
	s_cbranch_scc1 .Latt_nomask
	ds_read_b128 v[32:35], v101 offset:8192
	ds_read_b128 v[36:39], v101 offset:8224
	v_add_u32_e32 v130, s10, v95
	v_cmp_le_i32_e32 vcc, v130, v96
	v_add_u32_e32 v131, 2, v130
	s_waitcnt lgkmcnt(1)
	v_mfma_f32_32x32x16_bf16 v[48:63], v[32:35], v[72:75], 0
	ds_read_b128 v[32:35], v101 offset:8256
	ds_read_b128 v[106:109], v101 offset:8288
	v_add_u32_e32 v132, 3, v130
	v_add_u32_e32 v133, 8, v130
	v_add_u32_e32 v134, 9, v130
	s_mov_b32 s12, 0xf149f2ca
	s_waitcnt lgkmcnt(2)
	v_mfma_f32_32x32x16_bf16 v[48:63], v[36:39], v[64:67], v[48:63]
	s_waitcnt lgkmcnt(1)
	v_mfma_f32_32x32x16_bf16 v[48:63], v[32:35], v[68:71], v[48:63]
	ds_read_b128 v[32:35], v101 offset:12800
	ds_read_b128 v[110:113], v101 offset:12832
	ds_read_b128 v[114:117], v101 offset:12864
	ds_read_b128 v[118:121], v101 offset:12896
	ds_read_b128 v[122:125], v104
	ds_read_b128 v[126:129], v104 offset:32
	s_waitcnt lgkmcnt(6)
	v_mfma_f32_32x32x16_bf16 v[48:63], v[106:109], v[76:79], v[48:63]
	s_waitcnt lgkmcnt(5)
	v_mfma_f32_32x32x16_bf16 v[32:47], v[32:35], v[72:75], 0
	s_nop 9
	v_add_f32_e32 v48, v97, v48
	v_add_f32_e32 v49, v97, v49
	s_waitcnt lgkmcnt(1)
	v_sub_f32_e32 v48, v48, v122
	v_add_f32_e32 v50, v97, v50
	v_sub_f32_e32 v49, v49, v123
	v_cndmask_b32_e32 v106, v187, v48, vcc
	v_cmp_lt_i32_e32 vcc, v130, v96
	v_add_f32_e32 v51, v97, v51
	v_sub_f32_e32 v50, v50, v124
	v_cndmask_b32_e32 v107, v187, v49, vcc
	v_cmp_le_i32_e32 vcc, v131, v96
	v_add_f32_e32 v52, v97, v52
	v_sub_f32_e32 v51, v51, v125
	v_cndmask_b32_e32 v108, v187, v50, vcc
	v_cmp_le_i32_e32 vcc, v132, v96
	v_add_f32_e32 v53, v97, v53
	s_waitcnt lgkmcnt(0)
	v_sub_f32_e32 v52, v52, v126
	v_cndmask_b32_e32 v109, v187, v51, vcc
	v_cmp_le_i32_e32 vcc, v133, v96
	v_sub_f32_e32 v53, v53, v127
	v_add_f32_e32 v49, v97, v54
	v_cndmask_b32_e32 v122, v187, v52, vcc
	v_cmp_le_i32_e32 vcc, v134, v96
	v_add_u32_e32 v50, 10, v130
	v_sub_f32_e32 v49, v49, v128
	v_cndmask_b32_e32 v123, v187, v53, vcc
	v_cmp_le_i32_e32 vcc, v50, v96
	v_max3_f32 v48, v106, s12, v107
	v_mfma_f32_32x32x16_bf16 v[32:47], v[110:113], v[64:67], v[32:47]
	v_cndmask_b32_e32 v110, v187, v49, vcc
	v_add_f32_e32 v49, v97, v55
	v_add_u32_e32 v50, 11, v130
	v_max3_f32 v48, v48, v108, v109
	v_sub_f32_e32 v49, v49, v129
	v_cmp_le_i32_e32 vcc, v50, v96
	v_max3_f32 v48, v48, v122, v123
	v_add_u32_e32 v113, 16, v130
	v_cndmask_b32_e32 v111, v187, v49, vcc
	v_max3_f32 v112, v48, v110, v111
	ds_read_b128 v[48:51], v104 offset:64
	ds_read_b128 v[52:55], v104 offset:96
	v_add_f32_e32 v56, v97, v56
	v_cmp_le_i32_e32 vcc, v113, v96
	v_mfma_f32_32x32x16_bf16 v[32:47], v[114:117], v[68:71], v[32:47]
	s_waitcnt lgkmcnt(1)
	v_sub_f32_e32 v48, v56, v48
	v_cndmask_b32_e32 v56, v187, v48, vcc
	v_add_f32_e32 v48, v97, v57
	v_sub_f32_e32 v48, v48, v49
	v_add_u32_e32 v49, 17, v130
	v_cmp_le_i32_e32 vcc, v49, v96
	v_add_f32_e32 v49, v97, v58
	v_sub_f32_e32 v49, v49, v50
	v_add_u32_e32 v50, 18, v130
	v_cndmask_b32_e32 v57, v187, v48, vcc
	v_cmp_le_i32_e32 vcc, v50, v96
	v_add_u32_e32 v50, 19, v130
	v_max3_f32 v48, v112, v56, v57
	v_cndmask_b32_e32 v58, v187, v49, vcc
	v_add_f32_e32 v49, v97, v59
	v_sub_f32_e32 v49, v49, v51
	v_cmp_le_i32_e32 vcc, v50, v96
	v_add_f32_e32 v50, v97, v60
	s_waitcnt lgkmcnt(0)
	v_sub_f32_e32 v50, v50, v52
	v_cndmask_b32_e32 v59, v187, v49, vcc
	v_add_u32_e32 v49, 24, v130
	v_cmp_le_i32_e32 vcc, v49, v96
	v_add_f32_e32 v49, v97, v61
	v_sub_f32_e32 v49, v49, v53
	v_cndmask_b32_e32 v60, v187, v50, vcc
	v_add_u32_e32 v50, 25, v130
	v_cmp_le_i32_e32 vcc, v50, v96
	v_max3_f32 v48, v48, v58, v59
	v_mfma_f32_32x32x16_bf16 v[32:47], v[118:121], v[76:79], v[32:47]
	v_cndmask_b32_e32 v61, v187, v49, vcc
	v_max3_f32 v52, v48, v60, v61
	v_add_f32_e32 v48, v97, v62
	v_add_u32_e32 v49, 26, v130
	v_sub_f32_e32 v48, v48, v54
	v_cmp_le_i32_e32 vcc, v49, v96
	v_add_u32_e32 v49, 27, v130
	v_add_u32_e32 v113, 32, v130
	v_cndmask_b32_e32 v62, v187, v48, vcc
	v_add_f32_e32 v48, v97, v63
	v_sub_f32_e32 v48, v48, v55
	v_cmp_le_i32_e32 vcc, v49, v96
	v_add_f32_e32 v32, v97, v32
	v_add_f32_e32 v40, v97, v40
	v_cndmask_b32_e32 v63, v187, v48, vcc
	ds_read_b128 v[48:51], v104 offset:128
	v_max3_f32 v112, v52, v62, v63
	ds_read_b128 v[52:55], v104 offset:160
	v_cmp_le_i32_e32 vcc, v113, v96
	v_add_u32_e32 v113, 48, v130
	s_waitcnt lgkmcnt(1)
	v_sub_f32_e32 v32, v32, v48
	v_cndmask_b32_e32 v48, v187, v32, vcc
	v_add_f32_e32 v32, v97, v33
	v_add_u32_e32 v33, 33, v130
	v_sub_f32_e32 v32, v32, v49
	v_cmp_le_i32_e32 vcc, v33, v96
	v_add_f32_e32 v33, v97, v34
	v_add_u32_e32 v34, 34, v130
	v_cndmask_b32_e32 v49, v187, v32, vcc
	v_sub_f32_e32 v33, v33, v50
	v_cmp_le_i32_e32 vcc, v34, v96
	v_add_u32_e32 v34, 35, v130
	v_max3_f32 v32, v112, v48, v49
	v_cndmask_b32_e32 v50, v187, v33, vcc
	v_add_f32_e32 v33, v97, v35
	v_sub_f32_e32 v33, v33, v51
	v_cmp_le_i32_e32 vcc, v34, v96
	v_add_f32_e32 v34, v97, v36
	s_waitcnt lgkmcnt(0)
	v_sub_f32_e32 v34, v34, v52
	v_cndmask_b32_e32 v51, v187, v33, vcc
	v_add_u32_e32 v33, 40, v130
	v_cmp_le_i32_e32 vcc, v33, v96
	v_add_f32_e32 v33, v97, v37
	v_sub_f32_e32 v33, v33, v53
	v_cndmask_b32_e32 v52, v187, v34, vcc
	v_add_u32_e32 v34, 41, v130
	v_cmp_le_i32_e32 vcc, v34, v96
	v_max3_f32 v32, v32, v50, v51
	s_nop 0
	v_cndmask_b32_e32 v53, v187, v33, vcc
	v_max3_f32 v36, v32, v52, v53
	v_add_f32_e32 v32, v97, v38
	v_add_u32_e32 v33, 42, v130
	v_sub_f32_e32 v32, v32, v54
	v_cmp_le_i32_e32 vcc, v33, v96
	v_add_u32_e32 v33, 43, v130
	s_nop 0
	v_cndmask_b32_e32 v54, v187, v32, vcc
	v_add_f32_e32 v32, v97, v39
	v_sub_f32_e32 v32, v32, v55
	v_cmp_le_i32_e32 vcc, v33, v96
	s_nop 1
	v_cndmask_b32_e32 v55, v187, v32, vcc
	ds_read_b128 v[32:35], v104 offset:192
	v_max3_f32 v112, v36, v54, v55
	ds_read_b128 v[36:39], v104 offset:224
	v_cmp_le_i32_e32 vcc, v113, v96
	s_waitcnt lgkmcnt(1)
	v_sub_f32_e32 v32, v40, v32
	v_add_f32_e32 v40, v97, v41
	v_sub_f32_e32 v33, v40, v33
	v_add_u32_e32 v40, 49, v130
	v_add_f32_e32 v41, v97, v42
	v_cndmask_b32_e32 v32, v187, v32, vcc
	v_cmp_le_i32_e32 vcc, v40, v96
	v_sub_f32_e32 v34, v41, v34
	v_add_u32_e32 v41, 50, v130
	v_cndmask_b32_e32 v33, v187, v33, vcc
	v_cmp_le_i32_e32 vcc, v41, v96
	v_add_f32_e32 v41, v97, v43
	v_sub_f32_e32 v35, v41, v35
	v_add_u32_e32 v41, 51, v130
	v_cndmask_b32_e32 v34, v187, v34, vcc
	v_cmp_le_i32_e32 vcc, v41, v96
	v_add_u32_e32 v41, 56, v130
	v_add_f32_e32 v42, v97, v44
	v_cndmask_b32_e32 v35, v187, v35, vcc
	v_cmp_le_i32_e32 vcc, v41, v96
	v_add_f32_e32 v41, v97, v45
	s_waitcnt lgkmcnt(0)
	v_sub_f32_e32 v36, v42, v36
	v_sub_f32_e32 v37, v41, v37
	v_add_u32_e32 v41, 57, v130
	v_max3_f32 v40, v112, v32, v33
	v_cndmask_b32_e32 v36, v187, v36, vcc
	v_cmp_le_i32_e32 vcc, v41, v96
	v_max3_f32 v40, v40, v34, v35
	s_nop 0
	v_cndmask_b32_e32 v112, v187, v37, vcc
	v_max3_f32 v37, v40, v36, v112
	v_add_f32_e32 v40, v97, v46
	v_sub_f32_e32 v38, v40, v38
	v_add_u32_e32 v40, 58, v130
	v_cmp_le_i32_e32 vcc, v40, v96
	s_nop 1
	v_cndmask_b32_e32 v46, v187, v38, vcc
	v_add_f32_e32 v38, v97, v47
	v_sub_f32_e32 v38, v38, v39
	v_add_u32_e32 v39, 59, v130
	v_cmp_le_i32_e32 vcc, v39, v96
	s_nop 1
	v_cndmask_b32_e32 v47, v187, v38, vcc
	v_max3_f32 v37, v37, v46, v47
	ds_bpermute_b32 v38, v99, v37
	s_waitcnt lgkmcnt(0)
	v_max3_f32 v113, v105, v37, v38
	s_mov_b32 s99, 0x3fb8aa3b
	v_mul_f32_e32 v250, 0xbfb8aa3b, v113
	v_fma_f32 v38, v106, s99, v250
	v_exp_f32_e32 v38, v38
	v_fma_f32 v39, v107, s99, v250
	v_exp_f32_e32 v39, v39
	v_fma_f32 v40, v108, s99, v250
	v_exp_f32_e32 v40, v40
	v_fma_f32 v41, v109, s99, v250
	v_exp_f32_e32 v41, v41
	v_fma_f32 v43, v122, s99, v250
	v_add_f32_e32 v42, 0, v38
	v_exp_f32_e32 v43, v43
	v_fma_f32 v44, v123, s99, v250
	v_sub_f32_e32 v37, v105, v113
	v_add_f32_e32 v42, v39, v42
	v_exp_f32_e32 v44, v44
	v_fma_f32 v45, v110, s99, v250
	v_add_f32_e32 v42, v40, v42
	v_exp_f32_e32 v45, v45
	v_fma_f32 v105, v111, s99, v250
	v_add_f32_e32 v42, v41, v42
	v_exp_f32_e32 v105, v105
	v_fma_f32 v56, v56, s99, v250
	v_add_f32_e32 v42, v43, v42
	v_exp_f32_e32 v56, v56
	v_fma_f32 v57, v57, s99, v250
	v_add_f32_e32 v42, v44, v42
	v_exp_f32_e32 v57, v57
	v_fma_f32 v58, v58, s99, v250
	v_add_f32_e32 v42, v45, v42
	v_exp_f32_e32 v58, v58
	v_fma_f32 v59, v59, s99, v250
	v_add_f32_e32 v42, v105, v42
	v_exp_f32_e32 v59, v59
	v_fma_f32 v60, v60, s99, v250
	v_add_f32_e32 v42, v56, v42
	v_exp_f32_e32 v60, v60
	v_fma_f32 v61, v61, s99, v250
	v_add_f32_e32 v42, v57, v42
	v_exp_f32_e32 v61, v61
	v_fma_f32 v62, v62, s99, v250
	v_add_f32_e32 v42, v58, v42
	v_exp_f32_e32 v62, v62
	v_fma_f32 v63, v63, s99, v250
	v_add_f32_e32 v42, v59, v42
	v_exp_f32_e32 v63, v63
	v_add_f32_e32 v42, v60, v42
	v_add_f32_e32 v42, v61, v42
	v_add_f32_e32 v42, v62, v42
	v_add_f32_e32 v106, v63, v42
	v_fma_f32 v42, v48, s99, v250
	v_exp_f32_e32 v48, v42
	v_fma_f32 v32, v32, s99, v250
	v_fma_f32 v42, v49, s99, v250
	v_exp_f32_e32 v107, v32
	v_exp_f32_e32 v49, v42
	v_fma_f32 v32, v33, s99, v250
	v_fma_f32 v42, v50, s99, v250
	v_exp_f32_e32 v33, v32
	v_exp_f32_e32 v50, v42
	v_fma_f32 v32, v34, s99, v250
	v_fma_f32 v42, v51, s99, v250
	v_exp_f32_e32 v108, v32
	v_mul_f32_e32 v37, 0x3fb8aa3b, v37
	v_exp_f32_e32 v51, v42
	v_fma_f32 v32, v35, s99, v250
	v_fma_f32 v34, v36, s99, v250
	v_fma_f32 v42, v52, s99, v250
	v_exp_f32_e32 v109, v32
	v_exp_f32_e32 v32, v37
	v_exp_f32_e32 v110, v34
	ds_read2_b64 v[34:37], v102 offset0:128 offset1:130
	v_exp_f32_e32 v52, v42
	v_fma_f32 v42, v53, s99, v250
	v_exp_f32_e32 v53, v42
	v_fma_f32 v42, v54, s99, v250
	v_exp_f32_e32 v54, v42
	v_fma_f32 v42, v55, s99, v250
	v_exp_f32_e32 v55, v42
	v_cvt_pk_bf16_f32 v38, v38, v39
	v_cvt_pk_bf16_f32 v39, v40, v41
	v_cvt_pk_bf16_f32 v40, v43, v44
	v_cvt_pk_bf16_f32 v41, v45, v105
	ds_read2_b64 v[42:45], v103 offset0:192 offset1:194
	v_pk_mul_f32 v[30:31], v[30:31], v[32:33] op_sel_hi:[1,0]
	v_pk_mul_f32 v[28:29], v[28:29], v[32:33] op_sel_hi:[1,0]
	v_pk_mul_f32 v[26:27], v[26:27], v[32:33] op_sel_hi:[1,0]
	v_pk_mul_f32 v[24:25], v[24:25], v[32:33] op_sel_hi:[1,0]
	v_pk_mul_f32 v[22:23], v[22:23], v[32:33] op_sel_hi:[1,0]
	v_pk_mul_f32 v[20:21], v[20:21], v[32:33] op_sel_hi:[1,0]
	v_pk_mul_f32 v[18:19], v[18:19], v[32:33] op_sel_hi:[1,0]
	v_pk_mul_f32 v[16:17], v[16:17], v[32:33] op_sel_hi:[1,0]
	v_pk_mul_f32 v[14:15], v[14:15], v[32:33] op_sel_hi:[1,0]
	v_pk_mul_f32 v[12:13], v[12:13], v[32:33] op_sel_hi:[1,0]
	s_waitcnt lgkmcnt(1)
	v_mfma_f32_32x32x16_bf16 v[16:31], v[34:37], v[38:41], v[16:31]
	ds_read2_b64 v[34:37], v102 offset0:132 offset1:134
	v_mul_f32_e64 v10, v10, v32
	v_mul_f32_e64 v11, v11, v32
	v_mul_f32_e64 v8, v8, v32
	v_mul_f32_e64 v9, v9, v32
	v_pk_mul_f32 v[6:7], v[6:7], v[32:33] op_sel_hi:[1,0]
	v_pk_mul_f32 v[4:5], v[4:5], v[32:33] op_sel_hi:[1,0]
	v_pk_mul_f32 v[2:3], v[2:3], v[32:33] op_sel_hi:[1,0]
	v_pk_mul_f32 v[0:1], v[0:1], v[32:33] op_sel_hi:[1,0]
	s_waitcnt lgkmcnt(1)
	s_nop 0
	v_mfma_f32_32x32x16_bf16 v[0:15], v[42:45], v[38:41], v[0:15]
	v_fma_f32 v105, v112, s99, v250
	v_cvt_pk_bf16_f32 v38, v56, v57
	v_cvt_pk_bf16_f32 v39, v58, v59
	v_cvt_pk_bf16_f32 v40, v60, v61
	v_cvt_pk_bf16_f32 v41, v62, v63
	ds_read2_b64 v[42:45], v103 offset0:196 offset1:198
	v_add_f32_e32 v57, v48, v106
	s_waitcnt lgkmcnt(1)
	v_mfma_f32_32x32x16_bf16 v[16:31], v[34:37], v[38:41], v[16:31]
	v_fma_f32 v34, v46, s99, v250
	v_exp_f32_e32 v46, v34
	v_fma_f32 v47, v47, s99, v250
	ds_read2_b64 v[34:37], v102 offset0:136 offset1:138
	v_exp_f32_e32 v56, v105
	s_waitcnt lgkmcnt(1)
	v_mfma_f32_32x32x16_bf16 v[0:15], v[42:45], v[38:41], v[0:15]
	ds_read2_b64 v[42:45], v103 offset0:200 offset1:202
	v_cvt_pk_bf16_f32 v38, v48, v49
	v_cvt_pk_bf16_f32 v39, v50, v51
	v_cvt_pk_bf16_f32 v40, v52, v53
	v_cvt_pk_bf16_f32 v41, v54, v55
	v_exp_f32_e32 v47, v47
	v_mov_b32_e32 v105, v113
	s_waitcnt lgkmcnt(1)
	v_mfma_f32_32x32x16_bf16 v[16:31], v[34:37], v[38:41], v[16:31]
	v_add_f32_e32 v34, v49, v57
	v_add_f32_e32 v34, v50, v34
	v_add_f32_e32 v34, v51, v34
	v_add_f32_e32 v34, v52, v34
	v_add_f32_e32 v34, v53, v34
	v_add_f32_e32 v48, v54, v34
	ds_read2_b64 v[34:37], v102 offset0:140 offset1:142
	s_waitcnt lgkmcnt(1)
	v_mfma_f32_32x32x16_bf16 v[0:15], v[42:45], v[38:41], v[0:15]
	ds_read2_b64 v[42:45], v103 offset0:204 offset1:206
	v_add_f32_e32 v38, v55, v48
	v_add_f32_e32 v48, v107, v38
	v_cvt_pk_bf16_f32 v38, v107, v33
	v_cvt_pk_bf16_f32 v39, v108, v109
	v_cvt_pk_bf16_f32 v40, v110, v56
	v_cvt_pk_bf16_f32 v41, v46, v47
	v_add_f32_e32 v33, v33, v48
	v_add_f32_e32 v33, v108, v33
	s_waitcnt lgkmcnt(1)
	v_mfma_f32_32x32x16_bf16 v[16:31], v[34:37], v[38:41], v[16:31]
	v_add_f32_e32 v33, v109, v33
	v_add_f32_e32 v33, v110, v33
	v_add_f32_e32 v33, v56, v33
	v_add_f32_e32 v33, v46, v33
	v_add_f32_e32 v33, v47, v33
	v_fmac_f32_e32 v33, v100, v32
	v_mov_b32_e32 v100, v33
	s_waitcnt lgkmcnt(0)
	v_mfma_f32_32x32x16_bf16 v[0:15], v[42:45], v[38:41], v[0:15]
	s_branch .LBB0_934
.Latt_nomask:
	ds_read_b128 v[32:35], v101 offset:8192
	ds_read_b128 v[36:39], v101 offset:8224
	s_waitcnt lgkmcnt(1)
	v_mfma_f32_32x32x16_bf16 v[48:63], v[32:35], v[72:75], 0
	ds_read_b128 v[32:35], v101 offset:8256
	ds_read_b128 v[106:109], v101 offset:8288
	s_mov_b32 s12, 0xf149f2ca
	s_waitcnt lgkmcnt(2)
	v_mfma_f32_32x32x16_bf16 v[48:63], v[36:39], v[64:67], v[48:63]
	s_waitcnt lgkmcnt(1)
	v_mfma_f32_32x32x16_bf16 v[48:63], v[32:35], v[68:71], v[48:63]
	ds_read_b128 v[32:35], v101 offset:12800
	ds_read_b128 v[110:113], v101 offset:12832
	ds_read_b128 v[114:117], v101 offset:12864
	ds_read_b128 v[118:121], v101 offset:12896
	ds_read_b128 v[122:125], v104
	ds_read_b128 v[126:129], v104 offset:32
	s_waitcnt lgkmcnt(6)
	v_mfma_f32_32x32x16_bf16 v[48:63], v[106:109], v[76:79], v[48:63]
	s_waitcnt lgkmcnt(5)
	v_mfma_f32_32x32x16_bf16 v[32:47], v[32:35], v[72:75], 0
	s_nop 9
	v_add_f32_e32 v48, v97, v48
	v_add_f32_e32 v49, v97, v49
	s_waitcnt lgkmcnt(1)
	v_sub_f32_e32 v106, v48, v122
	v_add_f32_e32 v50, v97, v50
	v_sub_f32_e32 v107, v49, v123
	v_add_f32_e32 v51, v97, v51
	v_sub_f32_e32 v108, v50, v124
	v_add_f32_e32 v52, v97, v52
	v_sub_f32_e32 v109, v51, v125
	v_add_f32_e32 v53, v97, v53
	s_waitcnt lgkmcnt(0)
	v_sub_f32_e32 v122, v52, v126
	v_sub_f32_e32 v123, v53, v127
	v_add_f32_e32 v49, v97, v54
	v_sub_f32_e32 v49, v49, v128
	v_max3_f32 v48, v106, s12, v107
	v_mfma_f32_32x32x16_bf16 v[32:47], v[110:113], v[64:67], v[32:47]
	v_mov_b32_e32 v110, v49
	v_add_f32_e32 v49, v97, v55
	v_max3_f32 v48, v48, v108, v109
	v_sub_f32_e32 v111, v49, v129
	v_max3_f32 v48, v48, v122, v123
	v_max3_f32 v112, v48, v110, v111
	ds_read_b128 v[48:51], v104 offset:64
	ds_read_b128 v[52:55], v104 offset:96
	v_add_f32_e32 v56, v97, v56
	v_mfma_f32_32x32x16_bf16 v[32:47], v[114:117], v[68:71], v[32:47]
	s_waitcnt lgkmcnt(1)
	v_sub_f32_e32 v56, v56, v48
	v_add_f32_e32 v48, v97, v57
	v_sub_f32_e32 v57, v48, v49
	v_add_f32_e32 v49, v97, v58
	v_sub_f32_e32 v58, v49, v50
	v_max3_f32 v48, v112, v56, v57
	v_add_f32_e32 v49, v97, v59
	v_sub_f32_e32 v59, v49, v51
	v_add_f32_e32 v50, v97, v60
	s_waitcnt lgkmcnt(0)
	v_sub_f32_e32 v60, v50, v52
	v_add_f32_e32 v49, v97, v61
	v_sub_f32_e32 v61, v49, v53
	v_max3_f32 v48, v48, v58, v59
	v_mfma_f32_32x32x16_bf16 v[32:47], v[118:121], v[76:79], v[32:47]
	v_max3_f32 v52, v48, v60, v61
	v_add_f32_e32 v48, v97, v62
	v_sub_f32_e32 v62, v48, v54
	v_add_f32_e32 v48, v97, v63
	v_sub_f32_e32 v63, v48, v55
	s_nop 6
	v_add_f32_e32 v32, v97, v32
	v_add_f32_e32 v40, v97, v40
	ds_read_b128 v[48:51], v104 offset:128
	v_max3_f32 v112, v52, v62, v63
	ds_read_b128 v[52:55], v104 offset:160
	s_waitcnt lgkmcnt(1)
	v_sub_f32_e32 v48, v32, v48
	v_add_f32_e32 v32, v97, v33
	v_sub_f32_e32 v49, v32, v49
	v_add_f32_e32 v33, v97, v34
	v_sub_f32_e32 v50, v33, v50
	v_max3_f32 v32, v112, v48, v49
	v_add_f32_e32 v33, v97, v35
	v_sub_f32_e32 v51, v33, v51
	v_add_f32_e32 v34, v97, v36
	s_waitcnt lgkmcnt(0)
	v_sub_f32_e32 v52, v34, v52
	v_add_f32_e32 v33, v97, v37
	v_sub_f32_e32 v53, v33, v53
	v_max3_f32 v32, v32, v50, v51
	s_nop 0
	v_max3_f32 v36, v32, v52, v53
	v_add_f32_e32 v32, v97, v38
	v_sub_f32_e32 v54, v32, v54
	s_nop 0
	v_add_f32_e32 v32, v97, v39
	v_sub_f32_e32 v55, v32, v55
	s_nop 1
	ds_read_b128 v[32:35], v104 offset:192
	v_max3_f32 v112, v36, v54, v55
	ds_read_b128 v[36:39], v104 offset:224
	s_waitcnt lgkmcnt(1)
	v_sub_f32_e32 v32, v40, v32
	v_add_f32_e32 v40, v97, v41
	v_sub_f32_e32 v33, v40, v33
	v_add_f32_e32 v41, v97, v42
	v_sub_f32_e32 v34, v41, v34
	v_add_f32_e32 v41, v97, v43
	v_sub_f32_e32 v35, v41, v35
	v_add_f32_e32 v42, v97, v44
	v_add_f32_e32 v41, v97, v45
	s_waitcnt lgkmcnt(0)
	v_sub_f32_e32 v36, v42, v36
	v_sub_f32_e32 v37, v41, v37
	v_max3_f32 v40, v112, v32, v33
	v_max3_f32 v40, v40, v34, v35
	s_nop 0
	v_mov_b32_e32 v112, v37
	v_max3_f32 v37, v40, v36, v112
	v_add_f32_e32 v40, v97, v46
	v_sub_f32_e32 v46, v40, v38
	s_nop 1
	v_add_f32_e32 v38, v97, v47
	v_sub_f32_e32 v47, v38, v39
	s_nop 1
	v_max3_f32 v37, v37, v46, v47
	ds_bpermute_b32 v38, v99, v37
	s_waitcnt lgkmcnt(0)
	v_max3_f32 v113, v105, v37, v38
	s_mov_b32 s99, 0x3fb8aa3b
	v_mul_f32_e32 v250, 0xbfb8aa3b, v113
	v_fma_f32 v38, v106, s99, v250
	v_exp_f32_e32 v38, v38
	v_fma_f32 v39, v107, s99, v250
	v_exp_f32_e32 v39, v39
	v_fma_f32 v40, v108, s99, v250
	v_exp_f32_e32 v40, v40
	v_fma_f32 v41, v109, s99, v250
	v_exp_f32_e32 v41, v41
	v_fma_f32 v43, v122, s99, v250
	v_add_f32_e32 v42, 0, v38
	v_exp_f32_e32 v43, v43
	v_fma_f32 v44, v123, s99, v250
	v_sub_f32_e32 v37, v105, v113
	v_add_f32_e32 v42, v39, v42
	v_exp_f32_e32 v44, v44
	v_fma_f32 v45, v110, s99, v250
	v_add_f32_e32 v42, v40, v42
	v_exp_f32_e32 v45, v45
	v_fma_f32 v105, v111, s99, v250
	v_add_f32_e32 v42, v41, v42
	v_exp_f32_e32 v105, v105
	v_fma_f32 v56, v56, s99, v250
	v_add_f32_e32 v42, v43, v42
	v_exp_f32_e32 v56, v56
	v_fma_f32 v57, v57, s99, v250
	v_add_f32_e32 v42, v44, v42
	v_exp_f32_e32 v57, v57
	v_fma_f32 v58, v58, s99, v250
	v_add_f32_e32 v42, v45, v42
	v_exp_f32_e32 v58, v58
	v_fma_f32 v59, v59, s99, v250
	v_add_f32_e32 v42, v105, v42
	v_exp_f32_e32 v59, v59
	v_fma_f32 v60, v60, s99, v250
	v_add_f32_e32 v42, v56, v42
	v_exp_f32_e32 v60, v60
	v_fma_f32 v61, v61, s99, v250
	v_add_f32_e32 v42, v57, v42
	v_exp_f32_e32 v61, v61
	v_fma_f32 v62, v62, s99, v250
	v_add_f32_e32 v42, v58, v42
	v_exp_f32_e32 v62, v62
	v_fma_f32 v63, v63, s99, v250
	v_add_f32_e32 v42, v59, v42
	v_exp_f32_e32 v63, v63
	v_add_f32_e32 v42, v60, v42
	v_add_f32_e32 v42, v61, v42
	v_add_f32_e32 v42, v62, v42
	v_add_f32_e32 v106, v63, v42
	v_fma_f32 v42, v48, s99, v250
	v_exp_f32_e32 v48, v42
	v_fma_f32 v32, v32, s99, v250
	v_fma_f32 v42, v49, s99, v250
	v_exp_f32_e32 v107, v32
	v_exp_f32_e32 v49, v42
	v_fma_f32 v32, v33, s99, v250
	v_fma_f32 v42, v50, s99, v250
	v_exp_f32_e32 v33, v32
	v_exp_f32_e32 v50, v42
	v_fma_f32 v32, v34, s99, v250
	v_fma_f32 v42, v51, s99, v250
	v_exp_f32_e32 v108, v32
	v_mul_f32_e32 v37, 0x3fb8aa3b, v37
	v_exp_f32_e32 v51, v42
	v_fma_f32 v32, v35, s99, v250
	v_fma_f32 v34, v36, s99, v250
	v_fma_f32 v42, v52, s99, v250
	v_exp_f32_e32 v109, v32
	v_exp_f32_e32 v32, v37
	v_exp_f32_e32 v110, v34
	ds_read2_b64 v[34:37], v102 offset0:128 offset1:130
	v_exp_f32_e32 v52, v42
	v_fma_f32 v42, v53, s99, v250
	v_exp_f32_e32 v53, v42
	v_fma_f32 v42, v54, s99, v250
	v_exp_f32_e32 v54, v42
	v_fma_f32 v42, v55, s99, v250
	v_exp_f32_e32 v55, v42
	v_cvt_pk_bf16_f32 v38, v38, v39
	v_cvt_pk_bf16_f32 v39, v40, v41
	v_cvt_pk_bf16_f32 v40, v43, v44
	v_cvt_pk_bf16_f32 v41, v45, v105
	ds_read2_b64 v[42:45], v103 offset0:192 offset1:194
	v_pk_mul_f32 v[30:31], v[30:31], v[32:33] op_sel_hi:[1,0]
	v_pk_mul_f32 v[28:29], v[28:29], v[32:33] op_sel_hi:[1,0]
	v_pk_mul_f32 v[26:27], v[26:27], v[32:33] op_sel_hi:[1,0]
	v_pk_mul_f32 v[24:25], v[24:25], v[32:33] op_sel_hi:[1,0]
	v_pk_mul_f32 v[22:23], v[22:23], v[32:33] op_sel_hi:[1,0]
	v_pk_mul_f32 v[20:21], v[20:21], v[32:33] op_sel_hi:[1,0]
	v_pk_mul_f32 v[18:19], v[18:19], v[32:33] op_sel_hi:[1,0]
	v_pk_mul_f32 v[16:17], v[16:17], v[32:33] op_sel_hi:[1,0]
	v_pk_mul_f32 v[14:15], v[14:15], v[32:33] op_sel_hi:[1,0]
	v_pk_mul_f32 v[12:13], v[12:13], v[32:33] op_sel_hi:[1,0]
	s_waitcnt lgkmcnt(1)
	v_mfma_f32_32x32x16_bf16 v[16:31], v[34:37], v[38:41], v[16:31]
	ds_read2_b64 v[34:37], v102 offset0:132 offset1:134
	v_mul_f32_e64 v10, v10, v32
	v_mul_f32_e64 v11, v11, v32
	v_mul_f32_e64 v8, v8, v32
	v_mul_f32_e64 v9, v9, v32
	v_pk_mul_f32 v[6:7], v[6:7], v[32:33] op_sel_hi:[1,0]
	v_pk_mul_f32 v[4:5], v[4:5], v[32:33] op_sel_hi:[1,0]
	v_pk_mul_f32 v[2:3], v[2:3], v[32:33] op_sel_hi:[1,0]
	v_pk_mul_f32 v[0:1], v[0:1], v[32:33] op_sel_hi:[1,0]
	s_waitcnt lgkmcnt(1)
	s_nop 0
	v_mfma_f32_32x32x16_bf16 v[0:15], v[42:45], v[38:41], v[0:15]
	v_fma_f32 v105, v112, s99, v250
	v_cvt_pk_bf16_f32 v38, v56, v57
	v_cvt_pk_bf16_f32 v39, v58, v59
	v_cvt_pk_bf16_f32 v40, v60, v61
	v_cvt_pk_bf16_f32 v41, v62, v63
	ds_read2_b64 v[42:45], v103 offset0:196 offset1:198
	v_add_f32_e32 v57, v48, v106
	s_waitcnt lgkmcnt(1)
	v_mfma_f32_32x32x16_bf16 v[16:31], v[34:37], v[38:41], v[16:31]
	v_fma_f32 v34, v46, s99, v250
	v_exp_f32_e32 v46, v34
	v_fma_f32 v47, v47, s99, v250
	ds_read2_b64 v[34:37], v102 offset0:136 offset1:138
	v_exp_f32_e32 v56, v105
	s_waitcnt lgkmcnt(1)
	v_mfma_f32_32x32x16_bf16 v[0:15], v[42:45], v[38:41], v[0:15]
	ds_read2_b64 v[42:45], v103 offset0:200 offset1:202
	v_cvt_pk_bf16_f32 v38, v48, v49
	v_cvt_pk_bf16_f32 v39, v50, v51
	v_cvt_pk_bf16_f32 v40, v52, v53
	v_cvt_pk_bf16_f32 v41, v54, v55
	v_exp_f32_e32 v47, v47
	v_mov_b32_e32 v105, v113
	s_waitcnt lgkmcnt(1)
	v_mfma_f32_32x32x16_bf16 v[16:31], v[34:37], v[38:41], v[16:31]
	v_add_f32_e32 v34, v49, v57
	v_add_f32_e32 v34, v50, v34
	v_add_f32_e32 v34, v51, v34
	v_add_f32_e32 v34, v52, v34
	v_add_f32_e32 v34, v53, v34
	v_add_f32_e32 v48, v54, v34
	ds_read2_b64 v[34:37], v102 offset0:140 offset1:142
	s_waitcnt lgkmcnt(1)
	v_mfma_f32_32x32x16_bf16 v[0:15], v[42:45], v[38:41], v[0:15]
	ds_read2_b64 v[42:45], v103 offset0:204 offset1:206
	v_add_f32_e32 v38, v55, v48
	v_add_f32_e32 v48, v107, v38
	v_cvt_pk_bf16_f32 v38, v107, v33
	v_cvt_pk_bf16_f32 v39, v108, v109
	v_cvt_pk_bf16_f32 v40, v110, v56
	v_cvt_pk_bf16_f32 v41, v46, v47
	v_add_f32_e32 v33, v33, v48
	v_add_f32_e32 v33, v108, v33
	s_waitcnt lgkmcnt(1)
	v_mfma_f32_32x32x16_bf16 v[16:31], v[34:37], v[38:41], v[16:31]
	v_add_f32_e32 v33, v109, v33
	v_add_f32_e32 v33, v110, v33
	v_add_f32_e32 v33, v56, v33
	v_add_f32_e32 v33, v46, v33
	v_add_f32_e32 v33, v47, v33
	v_fmac_f32_e32 v33, v100, v32
	v_mov_b32_e32 v100, v33
	s_waitcnt lgkmcnt(0)
	v_mfma_f32_32x32x16_bf16 v[0:15], v[42:45], v[38:41], v[0:15]
	s_branch .LBB0_934
